# sc8 + P5 activation (ACT) epilogue stores marked non-temporal so they do not displace the K-loop A/B streams in L2
# baseline (speedup 1.0000x reference)
.LBB0_875:
	v_lshl_add_u32 v150, s71, 10, v148
	ds_read_b32 v151, v150
	s_lshl_b32 s23, s59, 7
	s_or_b32 s23, s23, s67
	s_ashr_i32 s28, s23, 6
	s_lshl_b32 s21, s14, 8
	s_waitcnt lgkmcnt(0)
	v_mul_f32_e32 v154, 0xbfb8aa3b, v151
	v_pk_mul_f32 v[156:157], v[80:81], v[154:155] op_sel_hi:[1,0]
	v_pk_mul_f32 v[158:159], v[78:79], v[154:155] op_sel_hi:[1,0]
	v_exp_f32_e32 v156, v156
	v_exp_f32_e32 v158, v158
	v_exp_f32_e32 v157, v157
	v_exp_f32_e32 v159, v159
	v_pk_mul_f32 v[80:81], v[100:101], v[80:81]
	v_pk_mul_f32 v[78:79], v[98:99], v[78:79]
	v_pk_add_f32 v[98:99], v[156:157], 1.0 op_sel_hi:[1,0]
	v_pk_add_f32 v[100:101], v[158:159], 1.0 op_sel_hi:[1,0]
	v_rcp_f32_e32 v98, v98
	v_rcp_f32_e32 v100, v100
	v_rcp_f32_e32 v99, v99
	v_rcp_f32_e32 v101, v101
	v_mul_f32_e32 v152, v151, v151
	v_pk_mul_f32 v[80:81], v[80:81], v[152:153] op_sel_hi:[1,0]
	v_pk_mul_f32 v[78:79], v[78:79], v[152:153] op_sel_hi:[1,0]
	v_pk_mul_f32 v[80:81], v[80:81], v[98:99]
	v_pk_mul_f32 v[78:79], v[78:79], v[100:101]
	v_pk_mul_f32 v[98:99], v[16:17], v[154:155] op_sel_hi:[1,0]
	v_pk_mul_f32 v[100:101], v[14:15], v[154:155] op_sel_hi:[1,0]
	v_exp_f32_e32 v98, v98
	v_exp_f32_e32 v100, v100
	v_exp_f32_e32 v99, v99
	v_exp_f32_e32 v101, v101
	v_pk_mul_f32 v[16:17], v[36:37], v[16:17]
	v_pk_mul_f32 v[14:15], v[34:35], v[14:15]
	v_pk_add_f32 v[34:35], v[98:99], 1.0 op_sel_hi:[1,0]
	v_pk_add_f32 v[36:37], v[100:101], 1.0 op_sel_hi:[1,0]
	v_rcp_f32_e32 v34, v34
	v_rcp_f32_e32 v36, v36
	v_rcp_f32_e32 v35, v35
	v_rcp_f32_e32 v37, v37
	s_ashr_i32 s29, s28, 31
	v_pk_mul_f32 v[16:17], v[16:17], v[152:153] op_sel_hi:[1,0]
	v_pk_mul_f32 v[14:15], v[14:15], v[152:153] op_sel_hi:[1,0]
	s_lshl_b64 s[28:29], s[28:29], 22
	v_pk_mul_f32 v[34:35], v[16:17], v[34:35]
	v_pk_mul_f32 v[16:17], v[14:15], v[36:37]
	v_add_u32_e32 v36, s21, v1
	v_ashrrev_i32_e32 v37, 31, v36
	s_add_u32 s28, s64, s28
	v_cvt_pk_bf16_f32 v14, v78, v79
	v_cvt_pk_bf16_f32 v15, v80, v81
	v_cvt_pk_bf16_f32 v16, v16, v17
	v_cvt_pk_bf16_f32 v17, v34, v35
	s_addc_u32 s29, s65, s29
	v_lshlrev_b64 v[34:35], 7, v[36:37]
	v_lshl_add_u64 v[34:35], s[28:29], 0, v[34:35]
	v_lshl_add_u64 v[34:35], v[34:35], 0, v[130:131]
	global_store_dwordx4 v[34:35], v[14:17], off nt
	v_mov_b32_e32 v151, s75
	ds_read_b128 v[78:81], v151
	ds_read_b128 v[14:17], v151
	ds_read_b128 v[98:101], v151
	ds_read_b128 v[34:37], v151
	ds_read_b32 v153, v150 offset:64
	s_andn2_b64 vcc, exec, s[6:7]
	s_waitcnt lgkmcnt(0)
	v_mul_f32_e32 v154, 0xbfb8aa3b, v153
	v_pk_mul_f32 v[156:157], v[68:69], v[154:155] op_sel_hi:[1,0]
	v_pk_mul_f32 v[158:159], v[66:67], v[154:155] op_sel_hi:[1,0]
	v_exp_f32_e32 v156, v156
	v_exp_f32_e32 v158, v158
	v_exp_f32_e32 v157, v157
	v_exp_f32_e32 v159, v159
	v_pk_mul_f32 v[68:69], v[84:85], v[68:69]
	v_pk_mul_f32 v[66:67], v[82:83], v[66:67]
	v_pk_add_f32 v[82:83], v[156:157], 1.0 op_sel_hi:[1,0]
	v_pk_add_f32 v[84:85], v[158:159], 1.0 op_sel_hi:[1,0]
	v_rcp_f32_e32 v82, v82
	v_rcp_f32_e32 v84, v84
	v_rcp_f32_e32 v83, v83
	v_rcp_f32_e32 v85, v85
	v_mul_f32_e32 v152, v153, v153
	v_pk_mul_f32 v[68:69], v[68:69], v[152:153] op_sel_hi:[1,0]
	v_pk_mul_f32 v[66:67], v[66:67], v[152:153] op_sel_hi:[1,0]
	v_pk_mul_f32 v[68:69], v[68:69], v[82:83]
	v_pk_mul_f32 v[66:67], v[66:67], v[84:85]
	v_pk_mul_f32 v[82:83], v[4:5], v[154:155] op_sel_hi:[1,0]
	v_pk_mul_f32 v[84:85], v[2:3], v[154:155] op_sel_hi:[1,0]
	v_exp_f32_e32 v82, v82
	v_exp_f32_e32 v84, v84
	v_exp_f32_e32 v83, v83
	v_exp_f32_e32 v85, v85
	v_pk_mul_f32 v[4:5], v[20:21], v[4:5]
	v_pk_mul_f32 v[2:3], v[18:19], v[2:3]
	v_pk_add_f32 v[18:19], v[82:83], 1.0 op_sel_hi:[1,0]
	v_pk_add_f32 v[20:21], v[84:85], 1.0 op_sel_hi:[1,0]
	v_rcp_f32_e32 v18, v18
	v_rcp_f32_e32 v20, v20
	v_rcp_f32_e32 v19, v19
	v_rcp_f32_e32 v21, v21
	v_pk_mul_f32 v[4:5], v[4:5], v[152:153] op_sel_hi:[1,0]
	v_pk_mul_f32 v[2:3], v[2:3], v[152:153] op_sel_hi:[1,0]
	v_pk_mul_f32 v[18:19], v[4:5], v[18:19]
	v_pk_mul_f32 v[4:5], v[2:3], v[20:21]
	v_add_u32_e32 v20, s21, v141
	v_ashrrev_i32_e32 v21, 31, v20
	v_cvt_pk_bf16_f32 v2, v66, v67
	v_cvt_pk_bf16_f32 v3, v68, v69
	v_cvt_pk_bf16_f32 v4, v4, v5
	v_cvt_pk_bf16_f32 v5, v18, v19
	v_lshlrev_b64 v[18:19], 7, v[20:21]
	v_lshl_add_u64 v[18:19], s[28:29], 0, v[18:19]
	v_lshl_add_u64 v[18:19], v[18:19], 0, v[130:131]
	global_store_dwordx4 v[18:19], v[2:5], off nt
	ds_read_b128 v[66:69], v151
	ds_read_b128 v[2:5], v151
	ds_read_b128 v[82:85], v151
	ds_read_b128 v[18:21], v151
	ds_read_b32 v153, v150 offset:128
	s_waitcnt lgkmcnt(0)
	v_mul_f32_e32 v154, 0xbfb8aa3b, v153
	v_pk_mul_f32 v[156:157], v[72:73], v[154:155] op_sel_hi:[1,0]
	v_pk_mul_f32 v[158:159], v[70:71], v[154:155] op_sel_hi:[1,0]
	v_exp_f32_e32 v156, v156
	v_exp_f32_e32 v158, v158
	v_exp_f32_e32 v157, v157
	v_exp_f32_e32 v159, v159
	v_pk_mul_f32 v[72:73], v[88:89], v[72:73]
	v_pk_mul_f32 v[70:71], v[86:87], v[70:71]
	v_pk_add_f32 v[86:87], v[156:157], 1.0 op_sel_hi:[1,0]
	v_pk_add_f32 v[88:89], v[158:159], 1.0 op_sel_hi:[1,0]
	v_rcp_f32_e32 v86, v86
	v_rcp_f32_e32 v88, v88
	v_rcp_f32_e32 v87, v87
	v_rcp_f32_e32 v89, v89
	v_mul_f32_e32 v152, v153, v153
	v_pk_mul_f32 v[72:73], v[72:73], v[152:153] op_sel_hi:[1,0]
	v_pk_mul_f32 v[70:71], v[70:71], v[152:153] op_sel_hi:[1,0]
	v_pk_mul_f32 v[72:73], v[72:73], v[86:87]
	v_pk_mul_f32 v[70:71], v[70:71], v[88:89]
	v_pk_mul_f32 v[86:87], v[8:9], v[154:155] op_sel_hi:[1,0]
	v_pk_mul_f32 v[88:89], v[6:7], v[154:155] op_sel_hi:[1,0]
	v_exp_f32_e32 v86, v86
	v_exp_f32_e32 v88, v88
	v_exp_f32_e32 v87, v87
	v_exp_f32_e32 v89, v89
	v_pk_mul_f32 v[8:9], v[24:25], v[8:9]
	v_pk_mul_f32 v[6:7], v[22:23], v[6:7]
	v_pk_add_f32 v[22:23], v[86:87], 1.0 op_sel_hi:[1,0]
	v_pk_add_f32 v[24:25], v[88:89], 1.0 op_sel_hi:[1,0]
	v_rcp_f32_e32 v22, v22
	v_rcp_f32_e32 v24, v24
	v_rcp_f32_e32 v23, v23
	v_rcp_f32_e32 v25, v25
	v_pk_mul_f32 v[8:9], v[8:9], v[152:153] op_sel_hi:[1,0]
	v_pk_mul_f32 v[6:7], v[6:7], v[152:153] op_sel_hi:[1,0]
	v_pk_mul_f32 v[22:23], v[8:9], v[22:23]
	v_pk_mul_f32 v[8:9], v[6:7], v[24:25]
	v_add_u32_e32 v24, s21, v142
	v_ashrrev_i32_e32 v25, 31, v24
	v_cvt_pk_bf16_f32 v6, v70, v71
	v_cvt_pk_bf16_f32 v7, v72, v73
	v_cvt_pk_bf16_f32 v8, v8, v9
	v_cvt_pk_bf16_f32 v9, v22, v23
	v_lshlrev_b64 v[22:23], 7, v[24:25]
	v_lshl_add_u64 v[22:23], s[28:29], 0, v[22:23]
	v_lshl_add_u64 v[22:23], v[22:23], 0, v[130:131]
	global_store_dwordx4 v[22:23], v[6:9], off nt
	ds_read_b128 v[70:73], v151
	ds_read_b128 v[6:9], v151
	ds_read_b128 v[86:89], v151
	ds_read_b128 v[22:25], v151
	ds_read_b32 v153, v150 offset:192
	s_waitcnt lgkmcnt(0)
	v_mul_f32_e32 v154, 0xbfb8aa3b, v153
	v_pk_mul_f32 v[156:157], v[76:77], v[154:155] op_sel_hi:[1,0]
	v_pk_mul_f32 v[158:159], v[74:75], v[154:155] op_sel_hi:[1,0]
	v_exp_f32_e32 v156, v156
	v_exp_f32_e32 v158, v158
	v_exp_f32_e32 v157, v157
	v_exp_f32_e32 v159, v159
	v_pk_mul_f32 v[76:77], v[96:97], v[76:77]
	v_pk_mul_f32 v[74:75], v[94:95], v[74:75]
	v_pk_add_f32 v[94:95], v[156:157], 1.0 op_sel_hi:[1,0]
	v_pk_add_f32 v[96:97], v[158:159], 1.0 op_sel_hi:[1,0]
	v_rcp_f32_e32 v94, v94
	v_rcp_f32_e32 v96, v96
	v_rcp_f32_e32 v95, v95
	v_rcp_f32_e32 v97, v97
	v_mul_f32_e32 v152, v153, v153
	v_pk_mul_f32 v[76:77], v[76:77], v[152:153] op_sel_hi:[1,0]
	v_pk_mul_f32 v[74:75], v[74:75], v[152:153] op_sel_hi:[1,0]
	v_pk_mul_f32 v[76:77], v[76:77], v[94:95]
	v_pk_mul_f32 v[74:75], v[74:75], v[96:97]
	v_pk_mul_f32 v[94:95], v[12:13], v[154:155] op_sel_hi:[1,0]
	v_pk_mul_f32 v[96:97], v[10:11], v[154:155] op_sel_hi:[1,0]
	v_exp_f32_e32 v94, v94
	v_exp_f32_e32 v96, v96
	v_exp_f32_e32 v95, v95
	v_exp_f32_e32 v97, v97
	v_pk_mul_f32 v[12:13], v[32:33], v[12:13]
	v_pk_mul_f32 v[10:11], v[30:31], v[10:11]
	v_pk_add_f32 v[30:31], v[94:95], 1.0 op_sel_hi:[1,0]
	v_pk_add_f32 v[32:33], v[96:97], 1.0 op_sel_hi:[1,0]
	v_rcp_f32_e32 v30, v30
	v_rcp_f32_e32 v32, v32
	v_rcp_f32_e32 v31, v31
	v_rcp_f32_e32 v33, v33
	v_pk_mul_f32 v[12:13], v[12:13], v[152:153] op_sel_hi:[1,0]
	v_pk_mul_f32 v[10:11], v[10:11], v[152:153] op_sel_hi:[1,0]
	v_pk_mul_f32 v[30:31], v[12:13], v[30:31]
	v_pk_mul_f32 v[12:13], v[10:11], v[32:33]
	v_add_u32_e32 v32, s21, v143
	v_ashrrev_i32_e32 v33, 31, v32
	v_cvt_pk_bf16_f32 v10, v74, v75
	v_cvt_pk_bf16_f32 v11, v76, v77
	v_cvt_pk_bf16_f32 v12, v12, v13
	v_cvt_pk_bf16_f32 v13, v30, v31
	v_lshlrev_b64 v[30:31], 7, v[32:33]
	v_lshl_add_u64 v[30:31], s[28:29], 0, v[30:31]
	v_lshl_add_u64 v[30:31], v[30:31], 0, v[130:131]
	global_store_dwordx4 v[30:31], v[10:13], off nt
	ds_read_b128 v[74:77], v151
	ds_read_b128 v[10:13], v151
	ds_read_b128 v[94:97], v151
	ds_read_b128 v[30:33], v151
	ds_read_b32 v153, v150 offset:512
	s_waitcnt lgkmcnt(0)
	v_mul_f32_e32 v154, 0xbfb8aa3b, v153
	v_pk_mul_f32 v[156:157], v[92:93], v[154:155] op_sel_hi:[1,0]
	v_pk_mul_f32 v[158:159], v[90:91], v[154:155] op_sel_hi:[1,0]
	v_exp_f32_e32 v156, v156
	v_exp_f32_e32 v158, v158
	v_exp_f32_e32 v157, v157
	v_exp_f32_e32 v159, v159
	v_pk_mul_f32 v[92:93], v[116:117], v[92:93]
	v_pk_mul_f32 v[90:91], v[114:115], v[90:91]
	v_pk_add_f32 v[114:115], v[156:157], 1.0 op_sel_hi:[1,0]
	v_pk_add_f32 v[116:117], v[158:159], 1.0 op_sel_hi:[1,0]
	v_rcp_f32_e32 v114, v114
	v_rcp_f32_e32 v116, v116
	v_rcp_f32_e32 v115, v115
	v_rcp_f32_e32 v117, v117
	v_mul_f32_e32 v152, v153, v153
	v_pk_mul_f32 v[92:93], v[92:93], v[152:153] op_sel_hi:[1,0]
	v_pk_mul_f32 v[90:91], v[90:91], v[152:153] op_sel_hi:[1,0]
	v_pk_mul_f32 v[92:93], v[92:93], v[114:115]
	v_pk_mul_f32 v[90:91], v[90:91], v[116:117]
	v_pk_mul_f32 v[114:115], v[28:29], v[154:155] op_sel_hi:[1,0]
	v_pk_mul_f32 v[116:117], v[26:27], v[154:155] op_sel_hi:[1,0]
	v_exp_f32_e32 v114, v114
	v_exp_f32_e32 v116, v116
	v_exp_f32_e32 v115, v115
	v_exp_f32_e32 v117, v117
	v_pk_mul_f32 v[28:29], v[52:53], v[28:29]
	v_pk_mul_f32 v[26:27], v[50:51], v[26:27]
	v_pk_add_f32 v[50:51], v[114:115], 1.0 op_sel_hi:[1,0]
	v_pk_add_f32 v[52:53], v[116:117], 1.0 op_sel_hi:[1,0]
	v_rcp_f32_e32 v50, v50
	v_rcp_f32_e32 v52, v52
	v_rcp_f32_e32 v51, v51
	v_rcp_f32_e32 v53, v53
	v_pk_mul_f32 v[28:29], v[28:29], v[152:153] op_sel_hi:[1,0]
	v_pk_mul_f32 v[26:27], v[26:27], v[152:153] op_sel_hi:[1,0]
	v_pk_mul_f32 v[50:51], v[28:29], v[50:51]
	v_pk_mul_f32 v[28:29], v[26:27], v[52:53]
	v_add_u32_e32 v52, s21, v144
	v_ashrrev_i32_e32 v53, 31, v52
	v_cvt_pk_bf16_f32 v26, v90, v91
	v_cvt_pk_bf16_f32 v27, v92, v93
	v_cvt_pk_bf16_f32 v28, v28, v29
	v_cvt_pk_bf16_f32 v29, v50, v51
	v_lshlrev_b64 v[50:51], 7, v[52:53]
	v_lshl_add_u64 v[50:51], s[28:29], 0, v[50:51]
	v_lshl_add_u64 v[50:51], v[50:51], 0, v[130:131]
	global_store_dwordx4 v[50:51], v[26:29], off nt
	ds_read_b128 v[90:93], v151
	ds_read_b128 v[26:29], v151
	ds_read_b128 v[114:117], v151
	ds_read_b128 v[50:53], v151
	ds_read_b32 v153, v150 offset:576
	s_waitcnt lgkmcnt(0)
	v_mul_f32_e32 v154, 0xbfb8aa3b, v153
	v_pk_mul_f32 v[156:157], v[104:105], v[154:155] op_sel_hi:[1,0]
	v_pk_mul_f32 v[158:159], v[102:103], v[154:155] op_sel_hi:[1,0]
	v_exp_f32_e32 v156, v156
	v_exp_f32_e32 v158, v158
	v_exp_f32_e32 v157, v157
	v_exp_f32_e32 v159, v159
	v_pk_mul_f32 v[104:105], v[120:121], v[104:105]
	v_pk_mul_f32 v[102:103], v[118:119], v[102:103]
	v_pk_add_f32 v[118:119], v[156:157], 1.0 op_sel_hi:[1,0]
	v_pk_add_f32 v[120:121], v[158:159], 1.0 op_sel_hi:[1,0]
	v_rcp_f32_e32 v118, v118
	v_rcp_f32_e32 v120, v120
	v_rcp_f32_e32 v119, v119
	v_rcp_f32_e32 v121, v121
	v_mul_f32_e32 v152, v153, v153
	v_pk_mul_f32 v[104:105], v[104:105], v[152:153] op_sel_hi:[1,0]
	v_pk_mul_f32 v[102:103], v[102:103], v[152:153] op_sel_hi:[1,0]
	v_pk_mul_f32 v[104:105], v[104:105], v[118:119]
	v_pk_mul_f32 v[102:103], v[102:103], v[120:121]
	v_pk_mul_f32 v[118:119], v[40:41], v[154:155] op_sel_hi:[1,0]
	v_pk_mul_f32 v[120:121], v[38:39], v[154:155] op_sel_hi:[1,0]
	v_exp_f32_e32 v118, v118
	v_exp_f32_e32 v120, v120
	v_exp_f32_e32 v119, v119
	v_exp_f32_e32 v121, v121
	v_pk_mul_f32 v[40:41], v[56:57], v[40:41]
	v_pk_mul_f32 v[38:39], v[54:55], v[38:39]
	v_pk_add_f32 v[54:55], v[118:119], 1.0 op_sel_hi:[1,0]
	v_pk_add_f32 v[56:57], v[120:121], 1.0 op_sel_hi:[1,0]
	v_rcp_f32_e32 v54, v54
	v_rcp_f32_e32 v56, v56
	v_rcp_f32_e32 v55, v55
	v_rcp_f32_e32 v57, v57
	v_pk_mul_f32 v[40:41], v[40:41], v[152:153] op_sel_hi:[1,0]
	v_pk_mul_f32 v[38:39], v[38:39], v[152:153] op_sel_hi:[1,0]
	v_pk_mul_f32 v[54:55], v[40:41], v[54:55]
	v_pk_mul_f32 v[40:41], v[38:39], v[56:57]
	v_add_u32_e32 v56, s21, v145
	v_ashrrev_i32_e32 v57, 31, v56
	v_cvt_pk_bf16_f32 v38, v102, v103
	v_cvt_pk_bf16_f32 v39, v104, v105
	v_cvt_pk_bf16_f32 v40, v40, v41
	v_cvt_pk_bf16_f32 v41, v54, v55
	v_lshlrev_b64 v[54:55], 7, v[56:57]
	v_lshl_add_u64 v[54:55], s[28:29], 0, v[54:55]
	v_lshl_add_u64 v[54:55], v[54:55], 0, v[130:131]
	global_store_dwordx4 v[54:55], v[38:41], off nt
	ds_read_b128 v[102:105], v151
	ds_read_b128 v[38:41], v151
	ds_read_b128 v[118:121], v151
	ds_read_b128 v[54:57], v151
	ds_read_b32 v153, v150 offset:640
	s_waitcnt lgkmcnt(0)
	v_mul_f32_e32 v154, 0xbfb8aa3b, v153
	v_pk_mul_f32 v[156:157], v[108:109], v[154:155] op_sel_hi:[1,0]
	v_pk_mul_f32 v[158:159], v[106:107], v[154:155] op_sel_hi:[1,0]
	v_exp_f32_e32 v156, v156
	v_exp_f32_e32 v158, v158
	v_exp_f32_e32 v157, v157
	v_exp_f32_e32 v159, v159
	v_pk_mul_f32 v[108:109], v[124:125], v[108:109]
	v_pk_mul_f32 v[106:107], v[122:123], v[106:107]
	v_pk_add_f32 v[122:123], v[156:157], 1.0 op_sel_hi:[1,0]
	v_pk_add_f32 v[124:125], v[158:159], 1.0 op_sel_hi:[1,0]
	v_rcp_f32_e32 v122, v122
	v_rcp_f32_e32 v124, v124
	v_rcp_f32_e32 v123, v123
	v_rcp_f32_e32 v125, v125
	v_mul_f32_e32 v152, v153, v153
	v_pk_mul_f32 v[108:109], v[108:109], v[152:153] op_sel_hi:[1,0]
	v_pk_mul_f32 v[106:107], v[106:107], v[152:153] op_sel_hi:[1,0]
	v_pk_mul_f32 v[108:109], v[108:109], v[122:123]
	v_pk_mul_f32 v[106:107], v[106:107], v[124:125]
	v_pk_mul_f32 v[122:123], v[44:45], v[154:155] op_sel_hi:[1,0]
	v_pk_mul_f32 v[124:125], v[42:43], v[154:155] op_sel_hi:[1,0]
	v_exp_f32_e32 v122, v122
	v_exp_f32_e32 v124, v124
	v_exp_f32_e32 v123, v123
	v_exp_f32_e32 v125, v125
	v_pk_mul_f32 v[44:45], v[60:61], v[44:45]
	v_pk_mul_f32 v[42:43], v[58:59], v[42:43]
	v_pk_add_f32 v[58:59], v[122:123], 1.0 op_sel_hi:[1,0]
	v_pk_add_f32 v[60:61], v[124:125], 1.0 op_sel_hi:[1,0]
	v_rcp_f32_e32 v58, v58
	v_rcp_f32_e32 v60, v60
	v_rcp_f32_e32 v59, v59
	v_rcp_f32_e32 v61, v61
	v_pk_mul_f32 v[44:45], v[44:45], v[152:153] op_sel_hi:[1,0]
	v_pk_mul_f32 v[42:43], v[42:43], v[152:153] op_sel_hi:[1,0]
	v_pk_mul_f32 v[58:59], v[44:45], v[58:59]
	v_pk_mul_f32 v[44:45], v[42:43], v[60:61]
	v_add_u32_e32 v60, s21, v146
	v_ashrrev_i32_e32 v61, 31, v60
	v_cvt_pk_bf16_f32 v42, v106, v107
	v_cvt_pk_bf16_f32 v43, v108, v109
	v_cvt_pk_bf16_f32 v44, v44, v45
	v_cvt_pk_bf16_f32 v45, v58, v59
	v_lshlrev_b64 v[58:59], 7, v[60:61]
	v_lshl_add_u64 v[58:59], s[28:29], 0, v[58:59]
	v_lshl_add_u64 v[58:59], v[58:59], 0, v[130:131]
	global_store_dwordx4 v[58:59], v[42:45], off nt
	ds_read_b128 v[106:109], v151
	ds_read_b128 v[42:45], v151
	ds_read_b128 v[122:125], v151
	ds_read_b128 v[58:61], v151
	ds_read_b32 v152, v150 offset:704
	s_waitcnt lgkmcnt(0)
	v_mul_f32_e32 v150, v152, v152
	v_mul_f32_e32 v152, 0xbfb8aa3b, v152
	v_pk_mul_f32 v[154:155], v[112:113], v[152:153] op_sel_hi:[1,0]
	v_pk_mul_f32 v[156:157], v[110:111], v[152:153] op_sel_hi:[1,0]
	v_exp_f32_e32 v154, v154
	v_exp_f32_e32 v156, v156
	v_exp_f32_e32 v155, v155
	v_exp_f32_e32 v157, v157
	v_pk_mul_f32 v[112:113], v[128:129], v[112:113]
	v_pk_mul_f32 v[110:111], v[126:127], v[110:111]
	v_pk_add_f32 v[126:127], v[154:155], 1.0 op_sel_hi:[1,0]
	v_pk_add_f32 v[128:129], v[156:157], 1.0 op_sel_hi:[1,0]
	v_rcp_f32_e32 v126, v126
	v_rcp_f32_e32 v128, v128
	v_rcp_f32_e32 v127, v127
	v_rcp_f32_e32 v129, v129
	v_pk_mul_f32 v[112:113], v[112:113], v[150:151] op_sel_hi:[1,0]
	v_pk_mul_f32 v[110:111], v[110:111], v[150:151] op_sel_hi:[1,0]
	v_pk_mul_f32 v[112:113], v[112:113], v[126:127]
	v_pk_mul_f32 v[110:111], v[110:111], v[128:129]
	v_pk_mul_f32 v[126:127], v[48:49], v[152:153] op_sel_hi:[1,0]
	v_pk_mul_f32 v[128:129], v[46:47], v[152:153] op_sel_hi:[1,0]
	v_exp_f32_e32 v126, v126
	v_exp_f32_e32 v128, v128
	v_exp_f32_e32 v127, v127
	v_exp_f32_e32 v129, v129
	v_pk_mul_f32 v[48:49], v[64:65], v[48:49]
	v_pk_mul_f32 v[46:47], v[62:63], v[46:47]
	v_pk_add_f32 v[62:63], v[126:127], 1.0 op_sel_hi:[1,0]
	v_pk_add_f32 v[64:65], v[128:129], 1.0 op_sel_hi:[1,0]
	v_rcp_f32_e32 v62, v62
	v_rcp_f32_e32 v64, v64
	v_rcp_f32_e32 v63, v63
	v_rcp_f32_e32 v65, v65
	v_pk_mul_f32 v[48:49], v[48:49], v[150:151] op_sel_hi:[1,0]
	v_pk_mul_f32 v[46:47], v[46:47], v[150:151] op_sel_hi:[1,0]
	v_pk_mul_f32 v[62:63], v[48:49], v[62:63]
	v_pk_mul_f32 v[48:49], v[46:47], v[64:65]
	v_add_u32_e32 v64, s21, v147
	v_ashrrev_i32_e32 v65, 31, v64
	v_cvt_pk_bf16_f32 v46, v110, v111
	v_cvt_pk_bf16_f32 v47, v112, v113
	v_cvt_pk_bf16_f32 v48, v48, v49
	v_cvt_pk_bf16_f32 v49, v62, v63
	v_lshlrev_b64 v[62:63], 7, v[64:65]
	v_lshl_add_u64 v[62:63], s[28:29], 0, v[62:63]
	v_lshl_add_u64 v[62:63], v[62:63], 0, v[130:131]
	global_store_dwordx4 v[62:63], v[46:49], off nt
	ds_read_b128 v[110:113], v151
	ds_read_b128 v[46:49], v151
	ds_read_b128 v[126:129], v151
	ds_read_b128 v[62:65], v151
	s_cbranch_vccnz .LBB0_867
	s_andn2_b64 vcc, exec, s[2:3]
	s_cbranch_vccnz .LBB0_866
	s_barrier
	s_branch .LBB0_866
